# attention loop: LDS read addresses of the next step computed ahead of the barrier (two address register pairs); VALU distribution unchanged
# speedup vs baseline: 1.0048x; 1.0048x over previous
.Lfa_sloop:
	s_add_i32 s76, s87, 2
	ds_read_b128 v[2:5], v230
	ds_read_b128 v[6:9], v230 offset:6656
	ds_read_b128 v[10:13], v230 offset:32
	ds_read_b128 v[198:201], v230 offset:6688
	ds_read_b128 v[202:205], v230 offset:64
	ds_read_b128 v[206:209], v230 offset:6720
	v_mfma_f32_32x32x16_bf16 v[64:79], v[210:213], v[234:237], v[64:79]
	v_exp_f32_e32 v96, v96
	v_exp_f32_e32 v97, v97
	v_add_f32_e32 v248, v248, v96
	v_exp_f32_e32 v98, v98
	v_mfma_f32_32x32x16_bf16 v[48:63], v[214:217], v[234:237], v[48:63]
	s_xor_b32 s1, s88, 0x6800
	s_add_i32 m0, s1, s66
	s_and_b64 vcc, exec, s[40:41]
	global_load_lds_dwordx4 v0, s[22:23]
	s_cbranch_vccnz .Lfa_as_nok
	s_add_i32 m0, s1, s78
	s_and_b64 vcc, exec, s[42:43]
	global_load_lds_dwordx4 v14, s[22:23]

; __device__ __forceinline__ void attn_unit(const Args& a, int l, int b, int h, int R0, bool special, LAS unsigned char* lds, float kb, int wv, bool pre, bool hasn, int nb, int nh, int nR0) {
;     ...
;     if (wave >= 4) __builtin_amdgcn_s_setprio(1);
.Lfa_as_nov:
	s_add_u32 s34, s34, 0x80
	s_addc_u32 s35, s35, 0
	v_add_f32_e32 v249, v249, v101
	v_exp_f32_e32 v103, v103
	v_add_f32_e32 v250, v250, v102
	v_add_f32_e32 v251, v251, v103
	s_waitcnt lgkmcnt(10)
	v_mfma_f32_32x32x16_bf16 v[128:143], v[2:5], v[156:159], v[32:47]
	v_cvt_pk_bf16_f32 v96, v96, v97
	v_cvt_pk_bf16_f32 v97, v98, v99
	v_cvt_pk_bf16_f32 v98, v100, v101
	v_cvt_pk_bf16_f32 v99, v102, v103
	v_mfma_f32_32x32x16_bf16 v[112:127], v[6:9], v[156:159], v[32:47]
	ds_read_b128 v[2:5], v231
	ds_read_b128 v[6:9], v231 offset:4608
	v_exp_f32_e32 v104, v104
	v_exp_f32_e32 v105, v105
	v_add_f32_e32 v248, v248, v104
	v_exp_f32_e32 v106, v106
	s_waitcnt lgkmcnt(10)
	v_mfma_f32_32x32x16_bf16 v[128:143], v[10:13], v[160:163], v[128:143]
	v_add_f32_e32 v249, v249, v105
	v_exp_f32_e32 v107, v107
	v_add_f32_e32 v250, v250, v106
	v_exp_f32_e32 v108, v108
	v_mfma_f32_32x32x16_bf16 v[112:127], v[198:201], v[160:163], v[112:127]
	ds_read_b128 v[10:13], v231 offset:32
	ds_read_b128 v[198:201], v231 offset:4640
	v_add_f32_e32 v251, v251, v107
	v_exp_f32_e32 v109, v109
	v_add_f32_e32 v248, v248, v108
	v_exp_f32_e32 v110, v110
	s_waitcnt lgkmcnt(10)
	v_mfma_f32_32x32x16_bf16 v[128:143], v[202:205], v[164:167], v[128:143]
	v_add_f32_e32 v249, v249, v109
	v_exp_f32_e32 v111, v111
	v_add_f32_e32 v250, v250, v110
	v_add_f32_e32 v251, v251, v111
	v_mfma_f32_32x32x16_bf16 v[112:127], v[206:209], v[164:167], v[112:127]
	v_cvt_pk_bf16_f32 v104, v104, v105
	v_cvt_pk_bf16_f32 v105, v106, v107
	v_cvt_pk_bf16_f32 v106, v108, v109
	v_cvt_pk_bf16_f32 v107, v110, v111
	s_waitcnt lgkmcnt(8)
	v_mfma_f32_32x32x16_bf16 v[128:143], v[210:213], v[144:147], v[128:143]
	v_exp_f32_e32 v80, v80
	v_exp_f32_e32 v81, v81
	v_add_f32_e32 v248, v248, v80
	v_exp_f32_e32 v82, v82
	v_mfma_f32_32x32x16_bf16 v[112:127], v[214:217], v[144:147], v[112:127]
	ds_read_b128 v[210:213], v231 offset:64
	ds_read_b128 v[214:217], v231 offset:4672
	v_add_f32_e32 v249, v249, v81
	v_exp_f32_e32 v83, v83
	v_add_f32_e32 v250, v250, v82
	v_exp_f32_e32 v84, v84
	s_waitcnt lgkmcnt(8)
	v_mfma_f32_32x32x16_bf16 v[128:143], v[218:221], v[148:151], v[128:143]
	v_add_f32_e32 v251, v251, v83
	v_exp_f32_e32 v85, v85
	v_add_f32_e32 v248, v248, v84
	v_exp_f32_e32 v86, v86
	v_mfma_f32_32x32x16_bf16 v[112:127], v[222:225], v[148:151], v[112:127]
	ds_read_b128 v[218:221], v231 offset:96
	ds_read_b128 v[222:225], v231 offset:4704
	v_add_f32_e32 v249, v249, v85
	v_exp_f32_e32 v87, v87
	v_add_f32_e32 v250, v250, v86
	v_add_f32_e32 v251, v251, v87
	s_waitcnt lgkmcnt(8)
	v_mfma_f32_32x32x16_bf16 v[128:143], v[234:237], v[152:155], v[128:143]
	v_exp_f32_e32 v88, v88
	v_exp_f32_e32 v89, v89
	v_add_f32_e32 v248, v248, v88
	v_exp_f32_e32 v90, v90
	v_mfma_f32_32x32x16_bf16 v[112:127], v[238:241], v[152:155], v[112:127]
	v_add_f32_e32 v249, v249, v89
	v_exp_f32_e32 v91, v91
	v_add_f32_e32 v250, v250, v90
	v_exp_f32_e32 v92, v92
	s_waitcnt lgkmcnt(6)
	v_mfma_f32_32x32x16_bf16 v[64:79], v[2:5], v[96:99], v[64:79]
	v_add_f32_e32 v251, v251, v91
	v_exp_f32_e32 v93, v93
	v_add_f32_e32 v248, v248, v92
	v_exp_f32_e32 v94, v94
	v_mfma_f32_32x32x16_bf16 v[48:63], v[6:9], v[96:99], v[48:63]
	v_add_f32_e32 v249, v249, v93
	v_exp_f32_e32 v95, v95
	v_add_f32_e32 v250, v250, v94
	v_add_f32_e32 v251, v251, v95
	s_waitcnt lgkmcnt(4)
	v_mfma_f32_32x32x16_bf16 v[64:79], v[10:13], v[104:107], v[64:79]
	v_cvt_pk_bf16_f32 v234, v80, v81
	v_cvt_pk_bf16_f32 v235, v82, v83
	v_cvt_pk_bf16_f32 v236, v84, v85
	v_cvt_pk_bf16_f32 v237, v86, v87
	v_mfma_f32_32x32x16_bf16 v[48:63], v[198:201], v[104:107], v[48:63]
	v_cvt_pk_bf16_f32 v238, v88, v89
	v_cvt_pk_bf16_f32 v239, v90, v91
	v_cvt_pk_bf16_f32 v240, v92, v93
	v_cvt_pk_bf16_f32 v241, v94, v95
	s_mov_b32 s1, s30
	s_add_i32 s30, s30, 0x2400
	s_cmp_eq_u32 s30, 0x6c00
	s_cselect_b32 s30, 0, s30
	s_mov_b32 s31, s1
	v_add_u32_e32 v191, s90, v190
	v_add_u32_e32 v192, s30, v247
	s_cmp_eq_u32 s75, 3
	s_cbranch_scc1 .Lfa_as_w3
	s_cmp_eq_u32 s75, 2
	s_cbranch_scc1 .Lfa_as_w2
	s_waitcnt vmcnt(4)
	s_branch .Lfa_as_wj

; __device__ __forceinline__ void attn_unit(const Args& a, int l, int b, int h, int R0, bool special, LAS unsigned char* lds, float kb, int wv, bool pre, bool hasn, int nb, int nh, int nR0) {
;     ...
;     if (wave >= 4) __builtin_amdgcn_s_setprio(1);
.Lfa_as_wj:
	s_waitcnt lgkmcnt(0)
	s_barrier
	ds_read_b128 v[2:5], v191
	ds_read_b128 v[6:9], v191 offset:6656
	ds_read_b128 v[10:13], v191 offset:32
	ds_read_b128 v[198:201], v191 offset:6688
	ds_read_b128 v[202:205], v191 offset:64
	ds_read_b128 v[206:209], v191 offset:6720
	v_mfma_f32_32x32x16_bf16 v[64:79], v[210:213], v[234:237], v[64:79]
	v_exp_f32_e32 v128, v128
	v_exp_f32_e32 v129, v129
	v_add_f32_e32 v248, v248, v128
	v_exp_f32_e32 v130, v130
	v_mfma_f32_32x32x16_bf16 v[48:63], v[214:217], v[234:237], v[48:63]
	s_xor_b32 s1, s90, 0xa800
	s_add_i32 m0, s1, s66
	s_and_b64 vcc, exec, s[40:41]
	global_load_lds_dwordx4 v0, s[22:23]
	s_cbranch_vccnz .Lfa_bs_nok
	s_add_i32 m0, s1, s78
	s_and_b64 vcc, exec, s[42:43]
	global_load_lds_dwordx4 v14, s[22:23]
.Lfa_bs_nok:
	s_add_u32 s22, s22, 0x3000
	s_addc_u32 s23, s23, 0
	v_add_f32_e32 v249, v249, v129
	v_exp_f32_e32 v131, v131
	v_add_f32_e32 v250, v250, v130
	v_exp_f32_e32 v132, v132
	v_mfma_f32_32x32x16_bf16 v[64:79], v[218:221], v[238:241], v[64:79]
	ds_read_b128 v[210:213], v191 offset:96
	ds_read_b128 v[214:217], v191 offset:6752
	v_add_f32_e32 v251, v251, v131
	v_exp_f32_e32 v133, v133
	v_add_f32_e32 v248, v248, v132
	v_exp_f32_e32 v134, v134
	v_mfma_f32_32x32x16_bf16 v[48:63], v[222:225], v[238:241], v[48:63]
	ds_read_b128 v[218:221], v191 offset:128
	ds_read_b128 v[222:225], v191 offset:6784
	ds_read_b128 v[234:237], v191 offset:160
	ds_read_b128 v[238:241], v191 offset:6816
	s_add_i32 s1, s31, s66
	s_add_i32 m0, s1, 0xd000
	s_and_b64 vcc, exec, s[42:43]
	global_load_lds_dwordx4 v15, s[34:35]
	s_cbranch_vccnz .Lfa_bs_nov
	s_add_i32 m0, s31, 0xf000
	s_nop 0
	global_load_lds_dwordx4 v197, s[34:35]
.Lfa_bs_nov:
	s_add_u32 s34, s34, 0x80
	s_addc_u32 s35, s35, 0
	v_add_f32_e32 v249, v249, v133
	v_exp_f32_e32 v135, v135
	v_add_f32_e32 v250, v250, v134
	v_add_f32_e32 v251, v251, v135
	s_waitcnt lgkmcnt(10)
	v_mfma_f32_32x32x16_bf16 v[96:111], v[2:5], v[156:159], v[32:47]
	v_cvt_pk_bf16_f32 v128, v128, v129
	v_cvt_pk_bf16_f32 v129, v130, v131
	v_cvt_pk_bf16_f32 v130, v132, v133
	v_cvt_pk_bf16_f32 v131, v134, v135
	v_mfma_f32_32x32x16_bf16 v[80:95], v[6:9], v[156:159], v[32:47]
	ds_read_b128 v[2:5], v192
	ds_read_b128 v[6:9], v192 offset:4608
	v_exp_f32_e32 v136, v136
	v_exp_f32_e32 v137, v137
	v_add_f32_e32 v248, v248, v136
	v_exp_f32_e32 v138, v138
	s_waitcnt lgkmcnt(10)
	v_mfma_f32_32x32x16_bf16 v[96:111], v[10:13], v[160:163], v[96:111]
	v_add_f32_e32 v249, v249, v137
	v_exp_f32_e32 v139, v139
	v_add_f32_e32 v250, v250, v138
	v_exp_f32_e32 v140, v140
	v_mfma_f32_32x32x16_bf16 v[80:95], v[198:201], v[160:163], v[80:95]
	ds_read_b128 v[10:13], v192 offset:32
	ds_read_b128 v[198:201], v192 offset:4640
	v_add_f32_e32 v251, v251, v139
	v_exp_f32_e32 v141, v141
	v_add_f32_e32 v248, v248, v140
	v_exp_f32_e32 v142, v142
	s_waitcnt lgkmcnt(10)
	v_mfma_f32_32x32x16_bf16 v[96:111], v[202:205], v[164:167], v[96:111]
	v_add_f32_e32 v249, v249, v141
	v_exp_f32_e32 v143, v143
	v_add_f32_e32 v250, v250, v142
	v_add_f32_e32 v251, v251, v143
	v_mfma_f32_32x32x16_bf16 v[80:95], v[206:209], v[164:167], v[80:95]
	v_cvt_pk_bf16_f32 v136, v136, v137
	v_cvt_pk_bf16_f32 v137, v138, v139
	v_cvt_pk_bf16_f32 v138, v140, v141
	v_cvt_pk_bf16_f32 v139, v142, v143
	s_waitcnt lgkmcnt(8)
	v_mfma_f32_32x32x16_bf16 v[96:111], v[210:213], v[144:147], v[96:111]
	v_exp_f32_e32 v112, v112
	v_exp_f32_e32 v113, v113
	v_add_f32_e32 v248, v248, v112
	v_exp_f32_e32 v114, v114
	v_mfma_f32_32x32x16_bf16 v[80:95], v[214:217], v[144:147], v[80:95]
	ds_read_b128 v[210:213], v192 offset:64
	ds_read_b128 v[214:217], v192 offset:4672
	v_add_f32_e32 v249, v249, v113
	v_exp_f32_e32 v115, v115
	v_add_f32_e32 v250, v250, v114
	v_exp_f32_e32 v116, v116
	s_waitcnt lgkmcnt(8)
	v_mfma_f32_32x32x16_bf16 v[96:111], v[218:221], v[148:151], v[96:111]
	v_add_f32_e32 v251, v251, v115
	v_exp_f32_e32 v117, v117
	v_add_f32_e32 v248, v248, v116
	v_exp_f32_e32 v118, v118
	v_mfma_f32_32x32x16_bf16 v[80:95], v[222:225], v[148:151], v[80:95]
	ds_read_b128 v[218:221], v192 offset:96
	ds_read_b128 v[222:225], v192 offset:4704
	v_add_f32_e32 v249, v249, v117
	v_exp_f32_e32 v119, v119
	v_add_f32_e32 v250, v250, v118
	v_add_f32_e32 v251, v251, v119
	s_waitcnt lgkmcnt(8)
	v_mfma_f32_32x32x16_bf16 v[96:111], v[234:237], v[152:155], v[96:111]
	v_exp_f32_e32 v120, v120
	v_exp_f32_e32 v121, v121
	v_add_f32_e32 v248, v248, v120
	v_exp_f32_e32 v122, v122
	v_mfma_f32_32x32x16_bf16 v[80:95], v[238:241], v[152:155], v[80:95]
	v_add_f32_e32 v249, v249, v121
	v_exp_f32_e32 v123, v123
	v_add_f32_e32 v250, v250, v122
	v_exp_f32_e32 v124, v124
	s_waitcnt lgkmcnt(6)
	v_mfma_f32_32x32x16_bf16 v[64:79], v[2:5], v[128:131], v[64:79]
	v_add_f32_e32 v251, v251, v123
	v_exp_f32_e32 v125, v125
	v_add_f32_e32 v248, v248, v124
	v_exp_f32_e32 v126, v126
	v_mfma_f32_32x32x16_bf16 v[48:63], v[6:9], v[128:131], v[48:63]
	v_add_f32_e32 v249, v249, v125
	v_exp_f32_e32 v127, v127
	v_add_f32_e32 v250, v250, v126
	v_add_f32_e32 v251, v251, v127
	s_waitcnt lgkmcnt(4)
	v_mfma_f32_32x32x16_bf16 v[64:79], v[10:13], v[136:139], v[64:79]
	v_cvt_pk_bf16_f32 v234, v112, v113
	v_cvt_pk_bf16_f32 v235, v114, v115
	v_cvt_pk_bf16_f32 v236, v116, v117
	v_cvt_pk_bf16_f32 v237, v118, v119
	v_mfma_f32_32x32x16_bf16 v[48:63], v[198:201], v[136:139], v[48:63]
	v_cvt_pk_bf16_f32 v238, v120, v121
	v_cvt_pk_bf16_f32 v239, v122, v123
	v_cvt_pk_bf16_f32 v240, v124, v125
	v_cvt_pk_bf16_f32 v241, v126, v127
	s_mov_b32 s1, s30
	s_add_i32 s30, s30, 0x2400
	s_cmp_eq_u32 s30, 0x6c00
	s_cselect_b32 s30, 0, s30
	s_mov_b32 s31, s1
	s_xor_b32 s88, s88, 0x6800
	v_add_u32_e32 v230, s88, v190
	v_add_u32_e32 v231, s30, v247
	s_cmp_eq_u32 s75, 3
	s_cbranch_scc1 .Lfa_bs_w3
	s_cmp_eq_u32 s75, 2
	s_cbranch_scc1 .Lfa_bs_w2
	s_waitcnt vmcnt(4)
	s_branch .Lfa_bs_wj

.Lfa_loop:
	s_add_i32 s76, s87, 2
	ds_read_b128 v[2:5], v230
	ds_read_b128 v[6:9], v230 offset:6656
	ds_read_b128 v[10:13], v230 offset:32
	ds_read_b128 v[198:201], v230 offset:6688
	ds_read_b128 v[202:205], v230 offset:64
	ds_read_b128 v[206:209], v230 offset:6720
	v_mfma_f32_32x32x16_bf16 v[64:79], v[210:213], v[234:237], v[64:79]
	v_exp_f32_e32 v96, v96
	v_exp_f32_e32 v97, v97
	v_add_f32_e32 v248, v248, v96
	v_exp_f32_e32 v98, v98
	v_mfma_f32_32x32x16_bf16 v[48:63], v[214:217], v[234:237], v[48:63]
	s_mov_b32 s96, 0
	s_cmp_gt_u32 s76, s73
	s_cbranch_scc1 .Lfa_a_nok
	s_xor_b32 s1, s88, 0x6800
	s_add_i32 m0, s1, s66
	s_mov_b32 s96, s75
	global_load_lds_dwordx4 v0, s[22:23]
	s_and_b64 vcc, exec, s[40:41]
	s_cbranch_vccnz .Lfa_a_nok
	s_add_i32 m0, s1, s78
	s_and_b64 vcc, exec, s[42:43]
	global_load_lds_dwordx4 v14, s[22:23]

; __device__ __forceinline__ void attn_unit(const Args& a, int l, int b, int h, int R0, bool special, LAS unsigned char* lds, float kb, int wv, bool pre, bool hasn, int nb, int nh, int nR0) {
;     ...
;     if (wave >= 4) __builtin_amdgcn_s_setprio(1);
.Lfa_a_nov:
	s_add_u32 s34, s34, 0x80
	s_addc_u32 s35, s35, 0
	v_add_f32_e32 v249, v249, v101
	v_exp_f32_e32 v103, v103
	v_add_f32_e32 v250, v250, v102
	v_add_f32_e32 v251, v251, v103
	s_waitcnt lgkmcnt(10)
	v_mfma_f32_32x32x16_bf16 v[128:143], v[2:5], v[156:159], v[32:47]
	v_cvt_pk_bf16_f32 v96, v96, v97
	v_cvt_pk_bf16_f32 v97, v98, v99
	v_cvt_pk_bf16_f32 v98, v100, v101
	v_cvt_pk_bf16_f32 v99, v102, v103
	v_mfma_f32_32x32x16_bf16 v[112:127], v[6:9], v[156:159], v[32:47]
	ds_read_b128 v[2:5], v231
	ds_read_b128 v[6:9], v231 offset:4608
	v_exp_f32_e32 v104, v104
	v_exp_f32_e32 v105, v105
	v_add_f32_e32 v248, v248, v104
	v_exp_f32_e32 v106, v106
	s_waitcnt lgkmcnt(10)
	v_mfma_f32_32x32x16_bf16 v[128:143], v[10:13], v[160:163], v[128:143]
	v_add_f32_e32 v249, v249, v105
	v_exp_f32_e32 v107, v107
	v_add_f32_e32 v250, v250, v106
	v_exp_f32_e32 v108, v108
	v_mfma_f32_32x32x16_bf16 v[112:127], v[198:201], v[160:163], v[112:127]
	ds_read_b128 v[10:13], v231 offset:32
	ds_read_b128 v[198:201], v231 offset:4640
	v_add_f32_e32 v251, v251, v107
	v_exp_f32_e32 v109, v109
	v_add_f32_e32 v248, v248, v108
	v_exp_f32_e32 v110, v110
	s_waitcnt lgkmcnt(10)
	v_mfma_f32_32x32x16_bf16 v[128:143], v[202:205], v[164:167], v[128:143]
	v_add_f32_e32 v249, v249, v109
	v_exp_f32_e32 v111, v111
	v_add_f32_e32 v250, v250, v110
	v_add_f32_e32 v251, v251, v111
	v_mfma_f32_32x32x16_bf16 v[112:127], v[206:209], v[164:167], v[112:127]
	v_cvt_pk_bf16_f32 v104, v104, v105
	v_cvt_pk_bf16_f32 v105, v106, v107
	v_cvt_pk_bf16_f32 v106, v108, v109
	v_cvt_pk_bf16_f32 v107, v110, v111
	s_waitcnt lgkmcnt(8)
	v_mfma_f32_32x32x16_bf16 v[128:143], v[210:213], v[144:147], v[128:143]
	v_exp_f32_e32 v80, v80
	v_exp_f32_e32 v81, v81
	v_add_f32_e32 v248, v248, v80
	v_exp_f32_e32 v82, v82
	v_mfma_f32_32x32x16_bf16 v[112:127], v[214:217], v[144:147], v[112:127]
	ds_read_b128 v[210:213], v231 offset:64
	ds_read_b128 v[214:217], v231 offset:4672
	v_add_f32_e32 v249, v249, v81
	v_exp_f32_e32 v83, v83
	v_add_f32_e32 v250, v250, v82
	v_exp_f32_e32 v84, v84
	s_waitcnt lgkmcnt(8)
	v_mfma_f32_32x32x16_bf16 v[128:143], v[218:221], v[148:151], v[128:143]
	v_add_f32_e32 v251, v251, v83
	v_exp_f32_e32 v85, v85
	v_add_f32_e32 v248, v248, v84
	v_exp_f32_e32 v86, v86
	v_mfma_f32_32x32x16_bf16 v[112:127], v[222:225], v[148:151], v[112:127]
	ds_read_b128 v[218:221], v231 offset:96
	ds_read_b128 v[222:225], v231 offset:4704
	v_add_f32_e32 v249, v249, v85
	v_exp_f32_e32 v87, v87
	v_add_f32_e32 v250, v250, v86
	v_add_f32_e32 v251, v251, v87
	s_waitcnt lgkmcnt(8)
	v_mfma_f32_32x32x16_bf16 v[128:143], v[234:237], v[152:155], v[128:143]
	v_exp_f32_e32 v88, v88
	v_exp_f32_e32 v89, v89
	v_add_f32_e32 v248, v248, v88
	v_exp_f32_e32 v90, v90
	v_mfma_f32_32x32x16_bf16 v[112:127], v[238:241], v[152:155], v[112:127]
	v_add_f32_e32 v249, v249, v89
	v_exp_f32_e32 v91, v91
	v_add_f32_e32 v250, v250, v90
	v_exp_f32_e32 v92, v92
	s_waitcnt lgkmcnt(6)
	v_mfma_f32_32x32x16_bf16 v[64:79], v[2:5], v[96:99], v[64:79]
	v_add_f32_e32 v251, v251, v91
	v_exp_f32_e32 v93, v93
	v_add_f32_e32 v248, v248, v92
	v_exp_f32_e32 v94, v94
	v_mfma_f32_32x32x16_bf16 v[48:63], v[6:9], v[96:99], v[48:63]
	v_add_f32_e32 v249, v249, v93
	v_exp_f32_e32 v95, v95
	v_add_f32_e32 v250, v250, v94
	v_add_f32_e32 v251, v251, v95
	s_waitcnt lgkmcnt(4)
	v_mfma_f32_32x32x16_bf16 v[64:79], v[10:13], v[104:107], v[64:79]
	v_cvt_pk_bf16_f32 v234, v80, v81
	v_cvt_pk_bf16_f32 v235, v82, v83
	v_cvt_pk_bf16_f32 v236, v84, v85
	v_cvt_pk_bf16_f32 v237, v86, v87
	v_mfma_f32_32x32x16_bf16 v[48:63], v[198:201], v[104:107], v[48:63]
	v_cvt_pk_bf16_f32 v238, v88, v89
	v_cvt_pk_bf16_f32 v239, v90, v91
	v_cvt_pk_bf16_f32 v240, v92, v93
	v_cvt_pk_bf16_f32 v241, v94, v95
	s_mov_b32 s1, s30
	s_add_i32 s30, s30, 0x2400
	s_cmp_eq_u32 s30, 0x6c00
	s_cselect_b32 s30, 0, s30
	s_mov_b32 s31, s1
	v_add_u32_e32 v191, s90, v190
	v_add_u32_e32 v192, s30, v247
	s_sub_i32 s0, s84, 64
	s_cmp_le_i32 s0, s74
	s_cbranch_scc0 .Lfa_mask_a

; __device__ __forceinline__ void attn_unit(const Args& a, int l, int b, int h, int R0, bool special, LAS unsigned char* lds, float kb, int wv, bool pre, bool hasn, int nb, int nh, int nR0) {
;     ...
;     if (wave >= 4) __builtin_amdgcn_s_setprio(1);
.Lfa_a_wj:
	s_waitcnt lgkmcnt(0)
	s_barrier
	ds_read_b128 v[2:5], v191
	ds_read_b128 v[6:9], v191 offset:6656
	ds_read_b128 v[10:13], v191 offset:32
	ds_read_b128 v[198:201], v191 offset:6688
	ds_read_b128 v[202:205], v191 offset:64
	ds_read_b128 v[206:209], v191 offset:6720
	v_mfma_f32_32x32x16_bf16 v[64:79], v[210:213], v[234:237], v[64:79]
	v_exp_f32_e32 v128, v128
	v_exp_f32_e32 v129, v129
	v_add_f32_e32 v248, v248, v128
	v_exp_f32_e32 v130, v130
	v_mfma_f32_32x32x16_bf16 v[48:63], v[214:217], v[234:237], v[48:63]
	s_mov_b32 s96, 0
	s_add_i32 s1, s76, 1
	s_cmp_gt_u32 s1, s73
	s_cbranch_scc1 .Lfa_b_nok
	s_xor_b32 s1, s90, 0xa800
	s_add_i32 m0, s1, s66
	s_mov_b32 s96, s75
	global_load_lds_dwordx4 v0, s[22:23]
	s_and_b64 vcc, exec, s[40:41]
	s_cbranch_vccnz .Lfa_b_nok
	s_add_i32 m0, s1, s78
	s_and_b64 vcc, exec, s[42:43]
	global_load_lds_dwordx4 v14, s[22:23]
.Lfa_b_nok:
	s_add_u32 s22, s22, 0x3000
	s_addc_u32 s23, s23, 0
	v_add_f32_e32 v249, v249, v129
	v_exp_f32_e32 v131, v131
	v_add_f32_e32 v250, v250, v130
	v_exp_f32_e32 v132, v132
	v_mfma_f32_32x32x16_bf16 v[64:79], v[218:221], v[238:241], v[64:79]
	ds_read_b128 v[210:213], v191 offset:96
	ds_read_b128 v[214:217], v191 offset:6752
	v_add_f32_e32 v251, v251, v131
	v_exp_f32_e32 v133, v133
	v_add_f32_e32 v248, v248, v132
	v_exp_f32_e32 v134, v134
	v_mfma_f32_32x32x16_bf16 v[48:63], v[222:225], v[238:241], v[48:63]
	ds_read_b128 v[218:221], v191 offset:128
	ds_read_b128 v[222:225], v191 offset:6784
	ds_read_b128 v[234:237], v191 offset:160
	ds_read_b128 v[238:241], v191 offset:6816
	s_cmp_gt_u32 s76, s73
	s_cbranch_scc1 .Lfa_b_nov
	s_add_i32 s1, s31, s66
	s_add_i32 m0, s1, 0xd000
	s_and_b64 vcc, exec, s[42:43]
	global_load_lds_dwordx4 v15, s[34:35]
	s_cbranch_vccnz .Lfa_b_nov
	s_add_i32 m0, s31, 0xf000
	s_nop 0
	global_load_lds_dwordx4 v197, s[34:35]
.Lfa_b_nov:
	s_add_u32 s34, s34, 0x80
	s_addc_u32 s35, s35, 0
	v_add_f32_e32 v249, v249, v133
	v_exp_f32_e32 v135, v135
	v_add_f32_e32 v250, v250, v134
	v_add_f32_e32 v251, v251, v135
	s_waitcnt lgkmcnt(10)
	v_mfma_f32_32x32x16_bf16 v[96:111], v[2:5], v[156:159], v[32:47]
	v_cvt_pk_bf16_f32 v128, v128, v129
	v_cvt_pk_bf16_f32 v129, v130, v131
	v_cvt_pk_bf16_f32 v130, v132, v133
	v_cvt_pk_bf16_f32 v131, v134, v135
	v_mfma_f32_32x32x16_bf16 v[80:95], v[6:9], v[156:159], v[32:47]
	ds_read_b128 v[2:5], v192
	ds_read_b128 v[6:9], v192 offset:4608
	v_exp_f32_e32 v136, v136
	v_exp_f32_e32 v137, v137
	v_add_f32_e32 v248, v248, v136
	v_exp_f32_e32 v138, v138
	s_waitcnt lgkmcnt(10)
	v_mfma_f32_32x32x16_bf16 v[96:111], v[10:13], v[160:163], v[96:111]
	v_add_f32_e32 v249, v249, v137
	v_exp_f32_e32 v139, v139
	v_add_f32_e32 v250, v250, v138
	v_exp_f32_e32 v140, v140
	v_mfma_f32_32x32x16_bf16 v[80:95], v[198:201], v[160:163], v[80:95]
	ds_read_b128 v[10:13], v192 offset:32
	ds_read_b128 v[198:201], v192 offset:4640
	v_add_f32_e32 v251, v251, v139
	v_exp_f32_e32 v141, v141
	v_add_f32_e32 v248, v248, v140
	v_exp_f32_e32 v142, v142
	s_waitcnt lgkmcnt(10)
	v_mfma_f32_32x32x16_bf16 v[96:111], v[202:205], v[164:167], v[96:111]
	v_add_f32_e32 v249, v249, v141
	v_exp_f32_e32 v143, v143
	v_add_f32_e32 v250, v250, v142
	v_add_f32_e32 v251, v251, v143
	v_mfma_f32_32x32x16_bf16 v[80:95], v[206:209], v[164:167], v[80:95]
	v_cvt_pk_bf16_f32 v136, v136, v137
	v_cvt_pk_bf16_f32 v137, v138, v139
	v_cvt_pk_bf16_f32 v138, v140, v141
	v_cvt_pk_bf16_f32 v139, v142, v143
	s_waitcnt lgkmcnt(8)
	v_mfma_f32_32x32x16_bf16 v[96:111], v[210:213], v[144:147], v[96:111]
	v_exp_f32_e32 v112, v112
	v_exp_f32_e32 v113, v113
	v_add_f32_e32 v248, v248, v112
	v_exp_f32_e32 v114, v114
	v_mfma_f32_32x32x16_bf16 v[80:95], v[214:217], v[144:147], v[80:95]
	ds_read_b128 v[210:213], v192 offset:64
	ds_read_b128 v[214:217], v192 offset:4672
	v_add_f32_e32 v249, v249, v113
	v_exp_f32_e32 v115, v115
	v_add_f32_e32 v250, v250, v114
	v_exp_f32_e32 v116, v116
	s_waitcnt lgkmcnt(8)
	v_mfma_f32_32x32x16_bf16 v[96:111], v[218:221], v[148:151], v[96:111]
	v_add_f32_e32 v251, v251, v115
	v_exp_f32_e32 v117, v117
	v_add_f32_e32 v248, v248, v116
	v_exp_f32_e32 v118, v118
	v_mfma_f32_32x32x16_bf16 v[80:95], v[222:225], v[148:151], v[80:95]
	ds_read_b128 v[218:221], v192 offset:96
	ds_read_b128 v[222:225], v192 offset:4704
	v_add_f32_e32 v249, v249, v117
	v_exp_f32_e32 v119, v119
	v_add_f32_e32 v250, v250, v118
	v_add_f32_e32 v251, v251, v119
	s_waitcnt lgkmcnt(8)
	v_mfma_f32_32x32x16_bf16 v[96:111], v[234:237], v[152:155], v[96:111]
	v_exp_f32_e32 v120, v120
	v_exp_f32_e32 v121, v121
	v_add_f32_e32 v248, v248, v120
	v_exp_f32_e32 v122, v122
	v_mfma_f32_32x32x16_bf16 v[80:95], v[238:241], v[152:155], v[80:95]
	v_add_f32_e32 v249, v249, v121
	v_exp_f32_e32 v123, v123
	v_add_f32_e32 v250, v250, v122
	v_exp_f32_e32 v124, v124
	s_waitcnt lgkmcnt(6)
	v_mfma_f32_32x32x16_bf16 v[64:79], v[2:5], v[128:131], v[64:79]
	v_add_f32_e32 v251, v251, v123
	v_exp_f32_e32 v125, v125
	v_add_f32_e32 v248, v248, v124
	v_exp_f32_e32 v126, v126
	v_mfma_f32_32x32x16_bf16 v[48:63], v[6:9], v[128:131], v[48:63]
	v_add_f32_e32 v249, v249, v125
	v_exp_f32_e32 v127, v127
	v_add_f32_e32 v250, v250, v126
	v_add_f32_e32 v251, v251, v127
	s_waitcnt lgkmcnt(4)
	v_mfma_f32_32x32x16_bf16 v[64:79], v[10:13], v[136:139], v[64:79]
	v_cvt_pk_bf16_f32 v234, v112, v113
	v_cvt_pk_bf16_f32 v235, v114, v115
	v_cvt_pk_bf16_f32 v236, v116, v117
	v_cvt_pk_bf16_f32 v237, v118, v119
	v_mfma_f32_32x32x16_bf16 v[48:63], v[198:201], v[136:139], v[48:63]
	v_cvt_pk_bf16_f32 v238, v120, v121
	v_cvt_pk_bf16_f32 v239, v122, v123
	v_cvt_pk_bf16_f32 v240, v124, v125
	v_cvt_pk_bf16_f32 v241, v126, v127
	s_mov_b32 s1, s30
	s_add_i32 s30, s30, 0x2400
	s_cmp_eq_u32 s30, 0x6c00
	s_cselect_b32 s30, 0, s30
	s_mov_b32 s31, s1
	s_xor_b32 s88, s88, 0x6800
	v_add_u32_e32 v230, s88, v190
	v_add_u32_e32 v231, s30, v247
	s_cmp_le_i32 s84, s74
	s_cbranch_scc0 .Lfa_mask_b
